# gqa-latent attention loop software-pipelined by one tile: S(t) MFMAs interleaved with exp/rowsum/cvt of tile t-1 (two score register sets), packed f32 row-sum adds
# speedup vs baseline: 1.0142x; 1.0063x over previous
.LBB0_1153:
	s_mul_i32 s70, s84, 0x9000
	v_add_u32_e32 v208, s70, v154
	s_mov_b32 s71, s65
	s_mul_i32 s68, s71, 0x9000
	s_mov_b32 s65, s84
	v_add_u32_e32 v209, s68, v155
	v_add_u32_e32 v210, 0x4000, v209
	v_add_u32_e32 v211, 0x5000, v209
	ds_read_b128 v[156:159], v208
	ds_read_b128 v[160:163], v208 offset:4608
	ds_read_b128 v[164:167], v208 offset:32
	ds_read_b128 v[168:171], v208 offset:4640
	ds_read_b128 v[172:175], v208 offset:64
	ds_read_b128 v[176:179], v208 offset:4672
	ds_read_b128 v[184:187], v208 offset:96
	ds_read_b128 v[188:191], v208 offset:4704
	s_waitcnt lgkmcnt(6)
	v_mfma_f32_32x32x16_bf16 v[64:79], v[156:159], v[108:111], v[32:47]
	ds_read2_b64 v[156:159], v210 offset0:128 offset1:130
	s_mul_i32 s72, s66, 0x9000
	s_add_i32 s73, s72, 0
	v_add3_u32 v218, s73, v150, v151
	v_add3_u32 v219, s73, v152, v153
	v_mfma_f32_32x32x16_bf16 v[80:95], v[160:163], v[108:111], v[32:47]
	ds_read2_b64 v[160:163], v211 offset0:192 offset1:194
	s_waitcnt vmcnt(0)
	ds_write_b128 v218, v[116:119]
	ds_write_b128 v219, v[124:127] offset:17408
	s_add_i32 s68, s25, -2
	s_cmp_gt_u32 s68, 33
	s_cbranch_scc1 .Lg4e_nogl
	s_cmp_lt_u32 s68, 30
	s_cselect_b64 s[74:75], -1, 0
	s_and_b64 s[76:77], s[74:75], exec
	s_cselect_b32 s68, 0, 0xffffffe0
	s_add_i32 s68, s68, s25
	s_and_b64 s[76:77], s[74:75], exec
	s_cselect_b32 s73, s21, s27
	s_cselect_b32 s78, s20, s26
	s_lshl_b64 s[76:77], s[68:69], 14
	s_add_u32 s76, s78, s76
	s_addc_u32 s77, s73, s77
	s_and_b64 s[78:79], s[74:75], exec
	s_cselect_b32 s73, s23, s64
	s_cselect_b32 s80, s22, s63
	s_lshl_b32 s68, s68, 6
	s_lshl_b64 s[78:79], s[68:69], 1
	s_add_u32 s78, s80, s78
	s_addc_u32 s79, s73, s79
	v_lshl_add_u64 v[222:223], v[142:143], 1, s[76:77]
	s_and_b64 s[74:75], s[74:75], exec
	v_lshl_add_u64 v[222:223], v[144:145], 1, v[222:223]
	s_cselect_b32 s68, 11, 8
	global_load_dwordx4 v[116:119], v[222:223], off
	v_lshlrev_b64 v[222:223], s68, v[146:147]
	v_lshl_add_u64 v[222:223], v[222:223], 1, s[78:79]
	v_lshl_add_u64 v[222:223], v[222:223], 0, v[128:129]
	global_load_dwordx4 v[124:127], v[222:223], off
.Lg4e_nogl:
	s_waitcnt lgkmcnt(8)
	v_mfma_f32_32x32x16_bf16 v[64:79], v[164:167], v[104:107], v[64:79]
	ds_read2_b64 v[164:167], v210 offset0:132 offset1:134
	v_mfma_f32_32x32x16_bf16 v[80:95], v[168:171], v[104:107], v[80:95]
	ds_read2_b64 v[168:171], v211 offset0:196 offset1:198
	s_waitcnt lgkmcnt(8)
	v_mfma_f32_32x32x16_bf16 v[64:79], v[172:175], v[100:103], v[64:79]
	ds_read2_b64 v[172:175], v210 offset0:136 offset1:138
	v_mfma_f32_32x32x16_bf16 v[80:95], v[176:179], v[100:103], v[80:95]
	ds_read2_b64 v[176:179], v211 offset0:200 offset1:202
	s_waitcnt lgkmcnt(8)
	v_mfma_f32_32x32x16_bf16 v[64:79], v[184:187], v[96:99], v[64:79]
	ds_read2_b64 v[184:187], v210 offset0:140 offset1:142
	v_mfma_f32_32x32x16_bf16 v[80:95], v[188:191], v[96:99], v[80:95]
	ds_read2_b64 v[188:191], v211 offset0:204 offset1:206
	s_waitcnt lgkmcnt(8)
	v_mfma_f32_32x32x16_bf16 v[16:31], v[156:159], v[134:137], v[16:31]
	v_mfma_f32_32x32x16_bf16 v[0:15], v[160:163], v[134:137], v[0:15]
	s_waitcnt lgkmcnt(4)
	v_mfma_f32_32x32x16_bf16 v[16:31], v[164:167], v[130:133], v[16:31]
	v_mfma_f32_32x32x16_bf16 v[0:15], v[168:171], v[130:133], v[0:15]
	s_waitcnt lgkmcnt(2)
	v_mfma_f32_32x32x16_bf16 v[16:31], v[172:175], v[120:123], v[16:31]
	v_mfma_f32_32x32x16_bf16 v[0:15], v[176:179], v[120:123], v[0:15]
	s_waitcnt lgkmcnt(0)
	v_mfma_f32_32x32x16_bf16 v[16:31], v[184:187], v[112:115], v[16:31]
	v_mfma_f32_32x32x16_bf16 v[0:15], v[188:191], v[112:115], v[0:15]
	v_max3_f32 v212, v64, v80, v68
	v_max3_f32 v213, v65, v81, v69
	v_max3_f32 v214, v66, v82, v70
	v_max3_f32 v215, v67, v83, v71
	v_max3_f32 v212, v212, v84, v72
	v_max3_f32 v213, v213, v85, v73
	v_max3_f32 v214, v214, v86, v74
	v_max3_f32 v215, v215, v87, v75
	v_max3_f32 v212, v212, v88, v76
	v_max3_f32 v213, v213, v89, v77
	v_max3_f32 v214, v214, v90, v78
	v_max3_f32 v215, v215, v91, v79
	v_max_f32_e32 v212, v212, v92
	v_max_f32_e32 v213, v213, v93
	v_max_f32_e32 v214, v214, v94
	v_max_f32_e32 v215, v215, v95
	v_max3_f32 v212, v212, v213, v214
	v_max_f32_e32 v212, v212, v215
	v_mov_b32_e32 v216, v212
	v_mov_b32_e32 v217, v212
	s_nop 1
	v_permlane32_swap_b32_e32 v216, v217
	v_max_f32_e32 v212, v216, v217
	v_cmp_lt_f32_e32 vcc, 0x41000000, v212
	s_cbranch_vccz .Lg4e_join
	v_max_f32_e32 v222, 0, v212
	v_add_f32_e32 v149, v149, v222
	v_exp_f32_e64 v216, -v222
	v_xor_b32_e32 v32, 0x80000000, v149
	v_pk_add_f32 v[64:65], v[64:65], v[222:223] op_sel_hi:[1,0] neg_lo:[0,1] neg_hi:[0,1]
	v_pk_add_f32 v[66:67], v[66:67], v[222:223] op_sel_hi:[1,0] neg_lo:[0,1] neg_hi:[0,1]
	v_pk_add_f32 v[68:69], v[68:69], v[222:223] op_sel_hi:[1,0] neg_lo:[0,1] neg_hi:[0,1]
	v_pk_add_f32 v[70:71], v[70:71], v[222:223] op_sel_hi:[1,0] neg_lo:[0,1] neg_hi:[0,1]
	v_pk_add_f32 v[72:73], v[72:73], v[222:223] op_sel_hi:[1,0] neg_lo:[0,1] neg_hi:[0,1]
	v_pk_add_f32 v[74:75], v[74:75], v[222:223] op_sel_hi:[1,0] neg_lo:[0,1] neg_hi:[0,1]
	v_pk_add_f32 v[76:77], v[76:77], v[222:223] op_sel_hi:[1,0] neg_lo:[0,1] neg_hi:[0,1]
	v_pk_add_f32 v[78:79], v[78:79], v[222:223] op_sel_hi:[1,0] neg_lo:[0,1] neg_hi:[0,1]
	v_pk_add_f32 v[80:81], v[80:81], v[222:223] op_sel_hi:[1,0] neg_lo:[0,1] neg_hi:[0,1]
	v_pk_add_f32 v[82:83], v[82:83], v[222:223] op_sel_hi:[1,0] neg_lo:[0,1] neg_hi:[0,1]
	v_pk_add_f32 v[84:85], v[84:85], v[222:223] op_sel_hi:[1,0] neg_lo:[0,1] neg_hi:[0,1]
	v_pk_add_f32 v[86:87], v[86:87], v[222:223] op_sel_hi:[1,0] neg_lo:[0,1] neg_hi:[0,1]
	v_pk_add_f32 v[88:89], v[88:89], v[222:223] op_sel_hi:[1,0] neg_lo:[0,1] neg_hi:[0,1]
	v_pk_add_f32 v[90:91], v[90:91], v[222:223] op_sel_hi:[1,0] neg_lo:[0,1] neg_hi:[0,1]
	v_pk_add_f32 v[92:93], v[92:93], v[222:223] op_sel_hi:[1,0] neg_lo:[0,1] neg_hi:[0,1]
	v_pk_add_f32 v[94:95], v[94:95], v[222:223] op_sel_hi:[1,0] neg_lo:[0,1] neg_hi:[0,1]
	v_mov_b32_e32 v33, v32
	v_mov_b32_e32 v34, v32
	v_mov_b32_e32 v35, v32
	v_mov_b32_e32 v36, v32
	v_mov_b32_e32 v37, v32
	v_mov_b32_e32 v38, v32
	v_mov_b32_e32 v39, v32
	v_mov_b32_e32 v40, v32
	v_mov_b32_e32 v41, v32
	v_mov_b32_e32 v42, v32
	v_mov_b32_e32 v43, v32
	v_mov_b32_e32 v44, v32
	v_mov_b32_e32 v45, v32
	v_mov_b32_e32 v46, v32
	v_mov_b32_e32 v47, v32
	v_mul_f32_e32 v148, v148, v216
	v_pk_mul_f32 v[16:17], v[16:17], v[216:217] op_sel_hi:[1,0]
	v_pk_mul_f32 v[18:19], v[18:19], v[216:217] op_sel_hi:[1,0]
	v_pk_mul_f32 v[20:21], v[20:21], v[216:217] op_sel_hi:[1,0]
	v_pk_mul_f32 v[22:23], v[22:23], v[216:217] op_sel_hi:[1,0]
	v_pk_mul_f32 v[24:25], v[24:25], v[216:217] op_sel_hi:[1,0]
	v_pk_mul_f32 v[26:27], v[26:27], v[216:217] op_sel_hi:[1,0]
	v_pk_mul_f32 v[28:29], v[28:29], v[216:217] op_sel_hi:[1,0]
	v_pk_mul_f32 v[30:31], v[30:31], v[216:217] op_sel_hi:[1,0]
	v_pk_mul_f32 v[0:1], v[0:1], v[216:217] op_sel_hi:[1,0]
	v_pk_mul_f32 v[2:3], v[2:3], v[216:217] op_sel_hi:[1,0]
	v_pk_mul_f32 v[4:5], v[4:5], v[216:217] op_sel_hi:[1,0]
	v_pk_mul_f32 v[6:7], v[6:7], v[216:217] op_sel_hi:[1,0]
	v_pk_mul_f32 v[8:9], v[8:9], v[216:217] op_sel_hi:[1,0]
	v_pk_mul_f32 v[10:11], v[10:11], v[216:217] op_sel_hi:[1,0]
	v_pk_mul_f32 v[12:13], v[12:13], v[216:217] op_sel_hi:[1,0]
	v_pk_mul_f32 v[14:15], v[14:15], v[216:217] op_sel_hi:[1,0]
.Lg4e_join:
	s_add_i32 s25, s25, 1
	s_barrier
	s_mov_b32 s84, s66
	s_mov_b32 s66, s71
.Lg4_loop:
	s_mul_i32 s70, s84, 0x9000
	v_add_u32_e32 v208, s70, v154
	s_mov_b32 s71, s65
	s_mul_i32 s68, s71, 0x9000
	s_mov_b32 s65, s84
	v_add_u32_e32 v209, s68, v155
	v_add_u32_e32 v210, 0x4000, v209
	v_add_u32_e32 v211, 0x5000, v209
	ds_read_b128 v[156:159], v208
	ds_read_b128 v[160:163], v208 offset:4608
	ds_read_b128 v[164:167], v208 offset:32
	ds_read_b128 v[168:171], v208 offset:4640
	ds_read_b128 v[172:175], v208 offset:64
	ds_read_b128 v[176:179], v208 offset:4672
	ds_read_b128 v[184:187], v208 offset:96
	ds_read_b128 v[188:191], v208 offset:4704
	s_waitcnt lgkmcnt(6)
	v_mfma_f32_32x32x16_bf16 v[48:63], v[156:159], v[108:111], v[32:47]
	ds_read2_b64 v[156:159], v210 offset0:128 offset1:130
	s_mul_i32 s72, s66, 0x9000
	s_add_i32 s73, s72, 0
	v_add3_u32 v218, s73, v150, v151
	v_add3_u32 v219, s73, v152, v153
	v_mfma_f32_32x32x16_bf16 v[192:207], v[160:163], v[108:111], v[32:47]
	ds_read2_b64 v[160:163], v211 offset0:192 offset1:194
	s_waitcnt vmcnt(0)
	ds_write_b128 v218, v[116:119]
	ds_write_b128 v219, v[124:127] offset:17408
	s_add_i32 s68, s25, -2
	s_cmp_gt_u32 s68, 33
	s_cbranch_scc1 .Lg4b_nogl
	s_cmp_lt_u32 s68, 30
	s_cselect_b64 s[74:75], -1, 0
	s_and_b64 s[76:77], s[74:75], exec
	s_cselect_b32 s68, 0, 0xffffffe0
	s_add_i32 s68, s68, s25
	s_and_b64 s[76:77], s[74:75], exec
	s_cselect_b32 s73, s21, s27
	s_cselect_b32 s78, s20, s26
	s_lshl_b64 s[76:77], s[68:69], 14
	s_add_u32 s76, s78, s76
	s_addc_u32 s77, s73, s77
	s_and_b64 s[78:79], s[74:75], exec
	s_cselect_b32 s73, s23, s64
	s_cselect_b32 s80, s22, s63
	s_lshl_b32 s68, s68, 6
	s_lshl_b64 s[78:79], s[68:69], 1
	s_add_u32 s78, s80, s78
	s_addc_u32 s79, s73, s79
	v_lshl_add_u64 v[222:223], v[142:143], 1, s[76:77]
	s_and_b64 s[74:75], s[74:75], exec
	v_lshl_add_u64 v[222:223], v[144:145], 1, v[222:223]
	s_cselect_b32 s68, 11, 8
	global_load_dwordx4 v[116:119], v[222:223], off
	v_lshlrev_b64 v[222:223], s68, v[146:147]
	v_lshl_add_u64 v[222:223], v[222:223], 1, s[78:79]
	v_lshl_add_u64 v[222:223], v[222:223], 0, v[128:129]
	global_load_dwordx4 v[124:127], v[222:223], off
.Lg4b_nogl:
	s_waitcnt lgkmcnt(8)
	v_mfma_f32_32x32x16_bf16 v[48:63], v[164:167], v[104:107], v[48:63]
	ds_read2_b64 v[164:167], v210 offset0:136 offset1:138
	v_exp_f32_e32 v64, v64
	v_exp_f32_e32 v80, v80
	v_exp_f32_e32 v65, v65
	v_exp_f32_e32 v81, v81
	v_exp_f32_e32 v66, v66
	v_mfma_f32_32x32x16_bf16 v[192:207], v[168:171], v[104:107], v[192:207]
	ds_read2_b64 v[168:171], v211 offset0:200 offset1:202
	v_pk_add_f32 v[214:215], v[64:65], v[80:81]
	v_exp_f32_e32 v82, v82
	v_exp_f32_e32 v67, v67
	v_exp_f32_e32 v83, v83
	s_waitcnt lgkmcnt(8)
	v_mfma_f32_32x32x16_bf16 v[48:63], v[172:175], v[100:103], v[48:63]
	ds_read2_b64 v[172:175], v210 offset0:132 offset1:134
	v_exp_f32_e32 v68, v68
	v_pk_add_f32 v[212:213], v[66:67], v[82:83]
	v_pk_add_f32 v[214:215], v[214:215], v[212:213]
	v_exp_f32_e32 v84, v84
	v_mfma_f32_32x32x16_bf16 v[192:207], v[176:179], v[100:103], v[192:207]
	ds_read2_b64 v[176:179], v211 offset0:196 offset1:198
	v_exp_f32_e32 v69, v69
	v_exp_f32_e32 v85, v85
	v_exp_f32_e32 v70, v70
	v_pk_add_f32 v[212:213], v[68:69], v[84:85]
	s_waitcnt lgkmcnt(8)
	v_mfma_f32_32x32x16_bf16 v[48:63], v[184:187], v[96:99], v[48:63]
	ds_read2_b64 v[184:187], v210 offset0:140 offset1:142
	v_pk_add_f32 v[214:215], v[214:215], v[212:213]
	v_exp_f32_e32 v86, v86
	v_exp_f32_e32 v71, v71
	v_exp_f32_e32 v87, v87
	v_mfma_f32_32x32x16_bf16 v[192:207], v[188:191], v[96:99], v[192:207]
	ds_read2_b64 v[188:191], v211 offset0:204 offset1:206
	v_cvt_pk_bf16_f32 v134, v64, v65
	v_pk_add_f32 v[212:213], v[70:71], v[86:87]
	v_pk_add_f32 v[214:215], v[214:215], v[212:213]
	v_cvt_pk_bf16_f32 v135, v66, v67
	v_cvt_pk_bf16_f32 v136, v68, v69
	v_cvt_pk_bf16_f32 v137, v70, v71
	s_waitcnt lgkmcnt(8)
	s_nop 0
	v_mfma_f32_32x32x16_bf16 v[16:31], v[156:159], v[134:137], v[16:31]
	v_cvt_pk_bf16_f32 v120, v80, v81
	v_cvt_pk_bf16_f32 v121, v82, v83
	v_cvt_pk_bf16_f32 v122, v84, v85
	v_cvt_pk_bf16_f32 v123, v86, v87
	v_mfma_f32_32x32x16_bf16 v[0:15], v[160:163], v[134:137], v[0:15]
	v_exp_f32_e32 v72, v72
	v_exp_f32_e32 v88, v88
	v_exp_f32_e32 v73, v73
	v_exp_f32_e32 v89, v89
	v_exp_f32_e32 v74, v74
	v_pk_add_f32 v[212:213], v[72:73], v[88:89]
	s_waitcnt lgkmcnt(4)
	v_mfma_f32_32x32x16_bf16 v[16:31], v[164:167], v[120:123], v[16:31]
	v_pk_add_f32 v[214:215], v[214:215], v[212:213]
	v_exp_f32_e32 v90, v90
	v_exp_f32_e32 v75, v75
	v_exp_f32_e32 v91, v91
	v_exp_f32_e32 v76, v76
	v_pk_add_f32 v[212:213], v[74:75], v[90:91]
	v_mfma_f32_32x32x16_bf16 v[0:15], v[168:171], v[120:123], v[0:15]
	v_pk_add_f32 v[214:215], v[214:215], v[212:213]
	v_exp_f32_e32 v92, v92
	v_exp_f32_e32 v77, v77
	v_exp_f32_e32 v93, v93
	v_exp_f32_e32 v78, v78
	v_pk_add_f32 v[212:213], v[76:77], v[92:93]
	v_pk_add_f32 v[214:215], v[214:215], v[212:213]
	v_exp_f32_e32 v94, v94
	v_exp_f32_e32 v79, v79
	v_exp_f32_e32 v95, v95
	v_cvt_pk_bf16_f32 v130, v72, v73
	v_pk_add_f32 v[212:213], v[78:79], v[94:95]
	v_pk_add_f32 v[214:215], v[214:215], v[212:213]
	v_cvt_pk_bf16_f32 v131, v74, v75
	v_cvt_pk_bf16_f32 v132, v76, v77
	v_cvt_pk_bf16_f32 v133, v78, v79
	s_waitcnt lgkmcnt(2)
	s_nop 0
	v_mfma_f32_32x32x16_bf16 v[16:31], v[172:175], v[130:133], v[16:31]
	v_cvt_pk_bf16_f32 v112, v88, v89
	v_cvt_pk_bf16_f32 v113, v90, v91
	v_cvt_pk_bf16_f32 v114, v92, v93
	v_cvt_pk_bf16_f32 v115, v94, v95
	v_add_f32_e32 v212, v214, v215
	v_add_f32_e32 v148, v148, v212
	v_mfma_f32_32x32x16_bf16 v[0:15], v[176:179], v[130:133], v[0:15]
	v_max3_f32 v212, v48, v192, v52
	v_max3_f32 v213, v49, v193, v53
	v_max3_f32 v214, v50, v194, v54
	v_max3_f32 v215, v51, v195, v55
	v_max3_f32 v212, v212, v196, v56
	v_max3_f32 v213, v213, v197, v57
	v_max3_f32 v214, v214, v198, v58
	v_max3_f32 v215, v215, v199, v59
	v_max3_f32 v212, v212, v200, v60
	s_waitcnt lgkmcnt(0)
	v_mfma_f32_32x32x16_bf16 v[16:31], v[184:187], v[112:115], v[16:31]
	v_max3_f32 v213, v213, v201, v61
	v_max3_f32 v214, v214, v202, v62
	v_max3_f32 v215, v215, v203, v63
	v_max_f32_e32 v212, v212, v204
	v_max_f32_e32 v213, v213, v205
	v_max_f32_e32 v214, v214, v206
	v_max_f32_e32 v215, v215, v207
	v_max3_f32 v212, v212, v213, v214
	v_max_f32_e32 v212, v212, v215
	v_mfma_f32_32x32x16_bf16 v[0:15], v[188:191], v[112:115], v[0:15]
	v_mov_b32_e32 v216, v212
	v_mov_b32_e32 v217, v212
	s_nop 1
	v_permlane32_swap_b32_e32 v216, v217
	v_max_f32_e32 v212, v216, v217
	v_cmp_lt_f32_e32 vcc, 0x41000000, v212
	s_cbranch_vccz .Lg4b_join
	v_max_f32_e32 v222, 0, v212
	v_add_f32_e32 v149, v149, v222
	v_exp_f32_e64 v216, -v222
	v_xor_b32_e32 v32, 0x80000000, v149
	v_pk_add_f32 v[48:49], v[48:49], v[222:223] op_sel_hi:[1,0] neg_lo:[0,1] neg_hi:[0,1]
	v_pk_add_f32 v[50:51], v[50:51], v[222:223] op_sel_hi:[1,0] neg_lo:[0,1] neg_hi:[0,1]
	v_pk_add_f32 v[52:53], v[52:53], v[222:223] op_sel_hi:[1,0] neg_lo:[0,1] neg_hi:[0,1]
	v_pk_add_f32 v[54:55], v[54:55], v[222:223] op_sel_hi:[1,0] neg_lo:[0,1] neg_hi:[0,1]
	v_pk_add_f32 v[56:57], v[56:57], v[222:223] op_sel_hi:[1,0] neg_lo:[0,1] neg_hi:[0,1]
	v_pk_add_f32 v[58:59], v[58:59], v[222:223] op_sel_hi:[1,0] neg_lo:[0,1] neg_hi:[0,1]
	v_pk_add_f32 v[60:61], v[60:61], v[222:223] op_sel_hi:[1,0] neg_lo:[0,1] neg_hi:[0,1]
	v_pk_add_f32 v[62:63], v[62:63], v[222:223] op_sel_hi:[1,0] neg_lo:[0,1] neg_hi:[0,1]
	v_pk_add_f32 v[192:193], v[192:193], v[222:223] op_sel_hi:[1,0] neg_lo:[0,1] neg_hi:[0,1]
	v_pk_add_f32 v[194:195], v[194:195], v[222:223] op_sel_hi:[1,0] neg_lo:[0,1] neg_hi:[0,1]
	v_pk_add_f32 v[196:197], v[196:197], v[222:223] op_sel_hi:[1,0] neg_lo:[0,1] neg_hi:[0,1]
	v_pk_add_f32 v[198:199], v[198:199], v[222:223] op_sel_hi:[1,0] neg_lo:[0,1] neg_hi:[0,1]
	v_pk_add_f32 v[200:201], v[200:201], v[222:223] op_sel_hi:[1,0] neg_lo:[0,1] neg_hi:[0,1]
	v_pk_add_f32 v[202:203], v[202:203], v[222:223] op_sel_hi:[1,0] neg_lo:[0,1] neg_hi:[0,1]
	v_pk_add_f32 v[204:205], v[204:205], v[222:223] op_sel_hi:[1,0] neg_lo:[0,1] neg_hi:[0,1]
	v_pk_add_f32 v[206:207], v[206:207], v[222:223] op_sel_hi:[1,0] neg_lo:[0,1] neg_hi:[0,1]
	v_mov_b32_e32 v33, v32
	v_mov_b32_e32 v34, v32
	v_mov_b32_e32 v35, v32
	v_mov_b32_e32 v36, v32
	v_mov_b32_e32 v37, v32
	v_mov_b32_e32 v38, v32
	v_mov_b32_e32 v39, v32
	v_mov_b32_e32 v40, v32
	v_mov_b32_e32 v41, v32
	v_mov_b32_e32 v42, v32
	v_mov_b32_e32 v43, v32
	v_mov_b32_e32 v44, v32
	v_mov_b32_e32 v45, v32
	v_mov_b32_e32 v46, v32
	v_mov_b32_e32 v47, v32
	v_mul_f32_e32 v148, v148, v216
	v_pk_mul_f32 v[16:17], v[16:17], v[216:217] op_sel_hi:[1,0]
	v_pk_mul_f32 v[18:19], v[18:19], v[216:217] op_sel_hi:[1,0]
	v_pk_mul_f32 v[20:21], v[20:21], v[216:217] op_sel_hi:[1,0]
	v_pk_mul_f32 v[22:23], v[22:23], v[216:217] op_sel_hi:[1,0]
	v_pk_mul_f32 v[24:25], v[24:25], v[216:217] op_sel_hi:[1,0]
	v_pk_mul_f32 v[26:27], v[26:27], v[216:217] op_sel_hi:[1,0]
	v_pk_mul_f32 v[28:29], v[28:29], v[216:217] op_sel_hi:[1,0]
	v_pk_mul_f32 v[30:31], v[30:31], v[216:217] op_sel_hi:[1,0]
	v_pk_mul_f32 v[0:1], v[0:1], v[216:217] op_sel_hi:[1,0]
	v_pk_mul_f32 v[2:3], v[2:3], v[216:217] op_sel_hi:[1,0]
	v_pk_mul_f32 v[4:5], v[4:5], v[216:217] op_sel_hi:[1,0]
	v_pk_mul_f32 v[6:7], v[6:7], v[216:217] op_sel_hi:[1,0]
	v_pk_mul_f32 v[8:9], v[8:9], v[216:217] op_sel_hi:[1,0]
	v_pk_mul_f32 v[10:11], v[10:11], v[216:217] op_sel_hi:[1,0]
	v_pk_mul_f32 v[12:13], v[12:13], v[216:217] op_sel_hi:[1,0]
	v_pk_mul_f32 v[14:15], v[14:15], v[216:217] op_sel_hi:[1,0]
.Lg4b_join:
	s_add_i32 s25, s25, 1
	s_cmp_lg_u32 s25, 37
	s_barrier
	s_cbranch_scc0 .Lg4_exit
	s_mov_b32 s84, s66
	s_mov_b32 s66, s71
	s_mul_i32 s70, s84, 0x9000
	v_add_u32_e32 v208, s70, v154
	s_mov_b32 s71, s65
	s_mul_i32 s68, s71, 0x9000
	s_mov_b32 s65, s84
	v_add_u32_e32 v209, s68, v155
	v_add_u32_e32 v210, 0x4000, v209
	v_add_u32_e32 v211, 0x5000, v209
	ds_read_b128 v[156:159], v208
	ds_read_b128 v[160:163], v208 offset:4608
	ds_read_b128 v[164:167], v208 offset:32
	ds_read_b128 v[168:171], v208 offset:4640
	ds_read_b128 v[172:175], v208 offset:64
	ds_read_b128 v[176:179], v208 offset:4672
	ds_read_b128 v[184:187], v208 offset:96
	ds_read_b128 v[188:191], v208 offset:4704
	s_waitcnt lgkmcnt(6)
	v_mfma_f32_32x32x16_bf16 v[64:79], v[156:159], v[108:111], v[32:47]
	ds_read2_b64 v[156:159], v210 offset0:128 offset1:130
	s_mul_i32 s72, s66, 0x9000
	s_add_i32 s73, s72, 0
	v_add3_u32 v218, s73, v150, v151
	v_add3_u32 v219, s73, v152, v153
	v_mfma_f32_32x32x16_bf16 v[80:95], v[160:163], v[108:111], v[32:47]
	ds_read2_b64 v[160:163], v211 offset0:192 offset1:194
	s_waitcnt vmcnt(0)
	ds_write_b128 v218, v[116:119]
	ds_write_b128 v219, v[124:127] offset:17408
	s_add_i32 s68, s25, -2
	s_cmp_gt_u32 s68, 33
	s_cbranch_scc1 .Lg4a_nogl
	s_cmp_lt_u32 s68, 30
	s_cselect_b64 s[74:75], -1, 0
	s_and_b64 s[76:77], s[74:75], exec
	s_cselect_b32 s68, 0, 0xffffffe0
	s_add_i32 s68, s68, s25
	s_and_b64 s[76:77], s[74:75], exec
	s_cselect_b32 s73, s21, s27
	s_cselect_b32 s78, s20, s26
	s_lshl_b64 s[76:77], s[68:69], 14
	s_add_u32 s76, s78, s76
	s_addc_u32 s77, s73, s77
	s_and_b64 s[78:79], s[74:75], exec
	s_cselect_b32 s73, s23, s64
	s_cselect_b32 s80, s22, s63
	s_lshl_b32 s68, s68, 6
	s_lshl_b64 s[78:79], s[68:69], 1
	s_add_u32 s78, s80, s78
	s_addc_u32 s79, s73, s79
	v_lshl_add_u64 v[222:223], v[142:143], 1, s[76:77]
	s_and_b64 s[74:75], s[74:75], exec
	v_lshl_add_u64 v[222:223], v[144:145], 1, v[222:223]
	s_cselect_b32 s68, 11, 8
	global_load_dwordx4 v[116:119], v[222:223], off
	v_lshlrev_b64 v[222:223], s68, v[146:147]
	v_lshl_add_u64 v[222:223], v[222:223], 1, s[78:79]
	v_lshl_add_u64 v[222:223], v[222:223], 0, v[128:129]
	global_load_dwordx4 v[124:127], v[222:223], off
.Lg4a_nogl:
	s_waitcnt lgkmcnt(8)
	v_mfma_f32_32x32x16_bf16 v[64:79], v[164:167], v[104:107], v[64:79]
	ds_read2_b64 v[164:167], v210 offset0:136 offset1:138
	v_exp_f32_e32 v48, v48
	v_exp_f32_e32 v192, v192
	v_exp_f32_e32 v49, v49
	v_exp_f32_e32 v193, v193
	v_exp_f32_e32 v50, v50
	v_mfma_f32_32x32x16_bf16 v[80:95], v[168:171], v[104:107], v[80:95]
	ds_read2_b64 v[168:171], v211 offset0:200 offset1:202
	v_pk_add_f32 v[214:215], v[48:49], v[192:193]
	v_exp_f32_e32 v194, v194
	v_exp_f32_e32 v51, v51
	v_exp_f32_e32 v195, v195
	s_waitcnt lgkmcnt(8)
	v_mfma_f32_32x32x16_bf16 v[64:79], v[172:175], v[100:103], v[64:79]
	ds_read2_b64 v[172:175], v210 offset0:132 offset1:134
	v_exp_f32_e32 v52, v52
	v_pk_add_f32 v[212:213], v[50:51], v[194:195]
	v_pk_add_f32 v[214:215], v[214:215], v[212:213]
	v_exp_f32_e32 v196, v196
	v_mfma_f32_32x32x16_bf16 v[80:95], v[176:179], v[100:103], v[80:95]
	ds_read2_b64 v[176:179], v211 offset0:196 offset1:198
	v_exp_f32_e32 v53, v53
	v_exp_f32_e32 v197, v197
	v_exp_f32_e32 v54, v54
	v_pk_add_f32 v[212:213], v[52:53], v[196:197]
	s_waitcnt lgkmcnt(8)
	v_mfma_f32_32x32x16_bf16 v[64:79], v[184:187], v[96:99], v[64:79]
	ds_read2_b64 v[184:187], v210 offset0:140 offset1:142
	v_pk_add_f32 v[214:215], v[214:215], v[212:213]
	v_exp_f32_e32 v198, v198
	v_exp_f32_e32 v55, v55
	v_exp_f32_e32 v199, v199
	v_mfma_f32_32x32x16_bf16 v[80:95], v[188:191], v[96:99], v[80:95]
	ds_read2_b64 v[188:191], v211 offset0:204 offset1:206
	v_cvt_pk_bf16_f32 v134, v48, v49
	v_pk_add_f32 v[212:213], v[54:55], v[198:199]
	v_pk_add_f32 v[214:215], v[214:215], v[212:213]
	v_cvt_pk_bf16_f32 v135, v50, v51
	v_cvt_pk_bf16_f32 v136, v52, v53
	v_cvt_pk_bf16_f32 v137, v54, v55
	s_waitcnt lgkmcnt(8)
	s_nop 0
	v_mfma_f32_32x32x16_bf16 v[16:31], v[156:159], v[134:137], v[16:31]
	v_cvt_pk_bf16_f32 v120, v192, v193
	v_cvt_pk_bf16_f32 v121, v194, v195
	v_cvt_pk_bf16_f32 v122, v196, v197
	v_cvt_pk_bf16_f32 v123, v198, v199
	v_mfma_f32_32x32x16_bf16 v[0:15], v[160:163], v[134:137], v[0:15]
	v_exp_f32_e32 v56, v56
	v_exp_f32_e32 v200, v200
	v_exp_f32_e32 v57, v57
	v_exp_f32_e32 v201, v201
	v_exp_f32_e32 v58, v58
	v_pk_add_f32 v[212:213], v[56:57], v[200:201]
	s_waitcnt lgkmcnt(4)
	v_mfma_f32_32x32x16_bf16 v[16:31], v[164:167], v[120:123], v[16:31]
	v_pk_add_f32 v[214:215], v[214:215], v[212:213]
	v_exp_f32_e32 v202, v202
	v_exp_f32_e32 v59, v59
	v_exp_f32_e32 v203, v203
	v_exp_f32_e32 v60, v60
	v_pk_add_f32 v[212:213], v[58:59], v[202:203]
	v_mfma_f32_32x32x16_bf16 v[0:15], v[168:171], v[120:123], v[0:15]
	v_pk_add_f32 v[214:215], v[214:215], v[212:213]
	v_exp_f32_e32 v204, v204
	v_exp_f32_e32 v61, v61
	v_exp_f32_e32 v205, v205
	v_exp_f32_e32 v62, v62
	v_pk_add_f32 v[212:213], v[60:61], v[204:205]
	v_pk_add_f32 v[214:215], v[214:215], v[212:213]
	v_exp_f32_e32 v206, v206
	v_exp_f32_e32 v63, v63
	v_exp_f32_e32 v207, v207
	v_cvt_pk_bf16_f32 v130, v56, v57
	v_pk_add_f32 v[212:213], v[62:63], v[206:207]
	v_pk_add_f32 v[214:215], v[214:215], v[212:213]
	v_cvt_pk_bf16_f32 v131, v58, v59
	v_cvt_pk_bf16_f32 v132, v60, v61
	v_cvt_pk_bf16_f32 v133, v62, v63
	s_waitcnt lgkmcnt(2)
	s_nop 0
	v_mfma_f32_32x32x16_bf16 v[16:31], v[172:175], v[130:133], v[16:31]
	v_cvt_pk_bf16_f32 v112, v200, v201
	v_cvt_pk_bf16_f32 v113, v202, v203
	v_cvt_pk_bf16_f32 v114, v204, v205
	v_cvt_pk_bf16_f32 v115, v206, v207
	v_add_f32_e32 v212, v214, v215
	v_add_f32_e32 v148, v148, v212
	v_mfma_f32_32x32x16_bf16 v[0:15], v[176:179], v[130:133], v[0:15]
	v_max3_f32 v212, v64, v80, v68
	v_max3_f32 v213, v65, v81, v69
	v_max3_f32 v214, v66, v82, v70
	v_max3_f32 v215, v67, v83, v71
	v_max3_f32 v212, v212, v84, v72
	v_max3_f32 v213, v213, v85, v73
	v_max3_f32 v214, v214, v86, v74
	v_max3_f32 v215, v215, v87, v75
	v_max3_f32 v212, v212, v88, v76
	s_waitcnt lgkmcnt(0)
	v_mfma_f32_32x32x16_bf16 v[16:31], v[184:187], v[112:115], v[16:31]
	v_max3_f32 v213, v213, v89, v77
	v_max3_f32 v214, v214, v90, v78
	v_max3_f32 v215, v215, v91, v79
	v_max_f32_e32 v212, v212, v92
	v_max_f32_e32 v213, v213, v93
	v_max_f32_e32 v214, v214, v94
	v_max_f32_e32 v215, v215, v95
	v_max3_f32 v212, v212, v213, v214
	v_max_f32_e32 v212, v212, v215
	v_mfma_f32_32x32x16_bf16 v[0:15], v[188:191], v[112:115], v[0:15]
	v_mov_b32_e32 v216, v212
	v_mov_b32_e32 v217, v212
	s_nop 1
	v_permlane32_swap_b32_e32 v216, v217
	v_max_f32_e32 v212, v216, v217
	v_cmp_lt_f32_e32 vcc, 0x41000000, v212
	s_cbranch_vccz .Lg4a_join
	v_max_f32_e32 v222, 0, v212
	v_add_f32_e32 v149, v149, v222
	v_exp_f32_e64 v216, -v222
	v_xor_b32_e32 v32, 0x80000000, v149
	v_pk_add_f32 v[64:65], v[64:65], v[222:223] op_sel_hi:[1,0] neg_lo:[0,1] neg_hi:[0,1]
	v_pk_add_f32 v[66:67], v[66:67], v[222:223] op_sel_hi:[1,0] neg_lo:[0,1] neg_hi:[0,1]
	v_pk_add_f32 v[68:69], v[68:69], v[222:223] op_sel_hi:[1,0] neg_lo:[0,1] neg_hi:[0,1]
	v_pk_add_f32 v[70:71], v[70:71], v[222:223] op_sel_hi:[1,0] neg_lo:[0,1] neg_hi:[0,1]
	v_pk_add_f32 v[72:73], v[72:73], v[222:223] op_sel_hi:[1,0] neg_lo:[0,1] neg_hi:[0,1]
	v_pk_add_f32 v[74:75], v[74:75], v[222:223] op_sel_hi:[1,0] neg_lo:[0,1] neg_hi:[0,1]
	v_pk_add_f32 v[76:77], v[76:77], v[222:223] op_sel_hi:[1,0] neg_lo:[0,1] neg_hi:[0,1]
	v_pk_add_f32 v[78:79], v[78:79], v[222:223] op_sel_hi:[1,0] neg_lo:[0,1] neg_hi:[0,1]
	v_pk_add_f32 v[80:81], v[80:81], v[222:223] op_sel_hi:[1,0] neg_lo:[0,1] neg_hi:[0,1]
	v_pk_add_f32 v[82:83], v[82:83], v[222:223] op_sel_hi:[1,0] neg_lo:[0,1] neg_hi:[0,1]
	v_pk_add_f32 v[84:85], v[84:85], v[222:223] op_sel_hi:[1,0] neg_lo:[0,1] neg_hi:[0,1]
	v_pk_add_f32 v[86:87], v[86:87], v[222:223] op_sel_hi:[1,0] neg_lo:[0,1] neg_hi:[0,1]
	v_pk_add_f32 v[88:89], v[88:89], v[222:223] op_sel_hi:[1,0] neg_lo:[0,1] neg_hi:[0,1]
	v_pk_add_f32 v[90:91], v[90:91], v[222:223] op_sel_hi:[1,0] neg_lo:[0,1] neg_hi:[0,1]
	v_pk_add_f32 v[92:93], v[92:93], v[222:223] op_sel_hi:[1,0] neg_lo:[0,1] neg_hi:[0,1]
	v_pk_add_f32 v[94:95], v[94:95], v[222:223] op_sel_hi:[1,0] neg_lo:[0,1] neg_hi:[0,1]
	v_mov_b32_e32 v33, v32
	v_mov_b32_e32 v34, v32
	v_mov_b32_e32 v35, v32
	v_mov_b32_e32 v36, v32
	v_mov_b32_e32 v37, v32
	v_mov_b32_e32 v38, v32
	v_mov_b32_e32 v39, v32
	v_mov_b32_e32 v40, v32
	v_mov_b32_e32 v41, v32
	v_mov_b32_e32 v42, v32
	v_mov_b32_e32 v43, v32
	v_mov_b32_e32 v44, v32
	v_mov_b32_e32 v45, v32
	v_mov_b32_e32 v46, v32
	v_mov_b32_e32 v47, v32
	v_mul_f32_e32 v148, v148, v216
	v_pk_mul_f32 v[16:17], v[16:17], v[216:217] op_sel_hi:[1,0]
	v_pk_mul_f32 v[18:19], v[18:19], v[216:217] op_sel_hi:[1,0]
	v_pk_mul_f32 v[20:21], v[20:21], v[216:217] op_sel_hi:[1,0]
	v_pk_mul_f32 v[22:23], v[22:23], v[216:217] op_sel_hi:[1,0]
	v_pk_mul_f32 v[24:25], v[24:25], v[216:217] op_sel_hi:[1,0]
	v_pk_mul_f32 v[26:27], v[26:27], v[216:217] op_sel_hi:[1,0]
	v_pk_mul_f32 v[28:29], v[28:29], v[216:217] op_sel_hi:[1,0]
	v_pk_mul_f32 v[30:31], v[30:31], v[216:217] op_sel_hi:[1,0]
	v_pk_mul_f32 v[0:1], v[0:1], v[216:217] op_sel_hi:[1,0]
	v_pk_mul_f32 v[2:3], v[2:3], v[216:217] op_sel_hi:[1,0]
	v_pk_mul_f32 v[4:5], v[4:5], v[216:217] op_sel_hi:[1,0]
	v_pk_mul_f32 v[6:7], v[6:7], v[216:217] op_sel_hi:[1,0]
	v_pk_mul_f32 v[8:9], v[8:9], v[216:217] op_sel_hi:[1,0]
	v_pk_mul_f32 v[10:11], v[10:11], v[216:217] op_sel_hi:[1,0]
	v_pk_mul_f32 v[12:13], v[12:13], v[216:217] op_sel_hi:[1,0]
	v_pk_mul_f32 v[14:15], v[14:15], v[216:217] op_sel_hi:[1,0]
.Lg4a_join:
	s_add_i32 s25, s25, 1
	s_barrier
	s_mov_b32 s84, s66
	s_mov_b32 s66, s71
	s_branch .Lg4_loop
.Lg4_exit:
	v_exp_f32_e32 v48, v48
	v_exp_f32_e32 v192, v192
	v_exp_f32_e32 v49, v49
	v_exp_f32_e32 v193, v193
	v_exp_f32_e32 v50, v50
	v_pk_add_f32 v[214:215], v[48:49], v[192:193]
	v_exp_f32_e32 v194, v194
	v_exp_f32_e32 v51, v51
	v_exp_f32_e32 v195, v195
	v_exp_f32_e32 v52, v52
	v_pk_add_f32 v[212:213], v[50:51], v[194:195]
	v_pk_add_f32 v[214:215], v[214:215], v[212:213]
	v_exp_f32_e32 v196, v196
	v_exp_f32_e32 v53, v53
	v_exp_f32_e32 v197, v197
	v_exp_f32_e32 v54, v54
	v_pk_add_f32 v[212:213], v[52:53], v[196:197]
	v_pk_add_f32 v[214:215], v[214:215], v[212:213]
	v_exp_f32_e32 v198, v198
	v_exp_f32_e32 v55, v55
	v_exp_f32_e32 v199, v199
	v_cvt_pk_bf16_f32 v134, v48, v49
	v_pk_add_f32 v[212:213], v[54:55], v[198:199]
	v_pk_add_f32 v[214:215], v[214:215], v[212:213]
	v_cvt_pk_bf16_f32 v135, v50, v51
	v_cvt_pk_bf16_f32 v136, v52, v53
	v_cvt_pk_bf16_f32 v137, v54, v55
	v_cvt_pk_bf16_f32 v120, v192, v193
	v_cvt_pk_bf16_f32 v121, v194, v195
	v_cvt_pk_bf16_f32 v122, v196, v197
	v_cvt_pk_bf16_f32 v123, v198, v199
	v_exp_f32_e32 v56, v56
	v_exp_f32_e32 v200, v200
	v_exp_f32_e32 v57, v57
	v_exp_f32_e32 v201, v201
	v_exp_f32_e32 v58, v58
	v_pk_add_f32 v[212:213], v[56:57], v[200:201]
	v_pk_add_f32 v[214:215], v[214:215], v[212:213]
	v_exp_f32_e32 v202, v202
	v_exp_f32_e32 v59, v59
	v_exp_f32_e32 v203, v203
	v_exp_f32_e32 v60, v60
	v_pk_add_f32 v[212:213], v[58:59], v[202:203]
	v_pk_add_f32 v[214:215], v[214:215], v[212:213]
	v_exp_f32_e32 v204, v204
	v_exp_f32_e32 v61, v61
	v_exp_f32_e32 v205, v205
	v_exp_f32_e32 v62, v62
	v_pk_add_f32 v[212:213], v[60:61], v[204:205]
	v_pk_add_f32 v[214:215], v[214:215], v[212:213]
	v_exp_f32_e32 v206, v206
	v_exp_f32_e32 v63, v63
	v_exp_f32_e32 v207, v207
	v_cvt_pk_bf16_f32 v130, v56, v57
	v_pk_add_f32 v[212:213], v[62:63], v[206:207]
	v_pk_add_f32 v[214:215], v[214:215], v[212:213]
	v_cvt_pk_bf16_f32 v131, v58, v59
	v_cvt_pk_bf16_f32 v132, v60, v61
	v_cvt_pk_bf16_f32 v133, v62, v63
	v_cvt_pk_bf16_f32 v112, v200, v201
	v_cvt_pk_bf16_f32 v113, v202, v203
	v_cvt_pk_bf16_f32 v114, v204, v205
	v_cvt_pk_bf16_f32 v115, v206, v207
	v_add_f32_e32 v212, v214, v215
	v_add_f32_e32 v148, v148, v212
	v_mov_b32_e32 v65, v148
	v_mov_b64_e32 v[48:49], v[32:33]
	v_mov_b64_e32 v[50:51], v[34:35]
	v_mov_b64_e32 v[52:53], v[36:37]
	v_mov_b64_e32 v[54:55], v[38:39]
	v_mov_b64_e32 v[56:57], v[40:41]
	v_mov_b64_e32 v[58:59], v[42:43]
	v_mov_b64_e32 v[60:61], v[44:45]
	v_mov_b64_e32 v[62:63], v[46:47]
